# retention chunk loop: loop-top wait relaxed to vmcnt(12) (K/V only) and the wait for the next chunk's Q fragments moved to just before the cross-term (vmcnt(10) / vmcnt(0) on the last chunk)
# speedup vs baseline: 1.0281x; 1.0015x over previous
.LBB0_117:
	s_waitcnt vmcnt(12)
	v_cvt_pk_bf16_f32 v104, v100, v101
	v_cvt_pk_bf16_f32 v105, v102, v103
	v_cvt_pk_bf16_f32 v106, v96, v97
	v_cvt_pk_bf16_f32 v107, v98, v99
	ds_write2_b64 v215, v[104:105], v[106:107] offset1:4
	v_cvt_pk_bf16_f32 v104, v92, v93
	v_cvt_pk_bf16_f32 v105, v94, v95
	v_cvt_pk_bf16_f32 v106, v88, v89
	v_cvt_pk_bf16_f32 v107, v90, v91
	ds_write2_b64 v215, v[104:105], v[106:107] offset0:8 offset1:12
	v_cvt_pk_bf16_f32 v104, v84, v85
	v_cvt_pk_bf16_f32 v105, v86, v87
	v_cvt_pk_bf16_f32 v106, v80, v81
	v_cvt_pk_bf16_f32 v107, v82, v83
	ds_write2_b64 v216, v[104:105], v[106:107] offset0:160 offset1:164
	v_cvt_pk_bf16_f32 v104, v76, v77
	v_cvt_pk_bf16_f32 v105, v78, v79
	v_cvt_pk_bf16_f32 v106, v72, v73
	v_cvt_pk_bf16_f32 v107, v74, v75
	ds_write2_b64 v216, v[104:105], v[106:107] offset0:168 offset1:172
	ds_write_b128 v217, v[0:3]
	ds_write_b128 v218, v[4:7]
	ds_write_b128 v219, v[8:11]
	ds_write_b128 v220, v[12:15]
	ds_write_b128 v221, v[28:31]
	ds_write_b128 v222, v[44:47]
	ds_write_b128 v223, v[56:59]
	ds_write_b128 v224, v[60:63]
	ds_write_b128 v225, v[64:67]
	v_lshlrev_b32_e32 v104, 16, v64
	v_and_b32_e32 v105, 0xffff0000, v64
	v_mul_f32_e32 v104, v246, v104
	v_mul_f32_e32 v105, v246, v105
	v_cvt_pk_bf16_f32 v104, v104, v105
	v_lshlrev_b32_e32 v105, 16, v65
	v_and_b32_e32 v106, 0xffff0000, v65
	v_mul_f32_e32 v105, v246, v105
	v_mul_f32_e32 v106, v246, v106
	v_cvt_pk_bf16_f32 v105, v105, v106
	v_lshlrev_b32_e32 v106, 16, v66
	v_and_b32_e32 v107, 0xffff0000, v66
	v_mul_f32_e32 v106, v246, v106
	v_mul_f32_e32 v107, v246, v107
	v_cvt_pk_bf16_f32 v106, v106, v107
	v_lshlrev_b32_e32 v107, 16, v67
	v_mul_f32_e32 v107, v246, v107
	v_and_b32_e32 v108, 0xffff0000, v67
	v_mul_f32_e32 v108, v246, v108
	v_cvt_pk_bf16_f32 v107, v107, v108
	ds_write_b128 v226, v[104:107]
	ds_write_b128 v227, v[68:71]
	v_lshlrev_b32_e32 v104, 16, v68
	v_and_b32_e32 v105, 0xffff0000, v68
	v_mul_f32_e32 v104, v247, v104
	v_mul_f32_e32 v105, v247, v105
	v_cvt_pk_bf16_f32 v104, v104, v105
	v_lshlrev_b32_e32 v105, 16, v69
	v_and_b32_e32 v106, 0xffff0000, v69
	v_mul_f32_e32 v105, v247, v105
	v_mul_f32_e32 v106, v247, v106
	v_cvt_pk_bf16_f32 v105, v105, v106
	v_lshlrev_b32_e32 v106, 16, v70
	v_and_b32_e32 v107, 0xffff0000, v70
	s_add_i32 s51, s52, 1
	v_mul_f32_e32 v106, v247, v106
	v_mul_f32_e32 v107, v247, v107
	s_cmp_ge_u32 s51, s45
	v_cvt_pk_bf16_f32 v106, v106, v107
	v_lshlrev_b32_e32 v107, 16, v71
	s_cselect_b64 s[12:13], -1, 0
	s_cmp_lt_u32 s51, s45
	v_mul_f32_e32 v107, v247, v107
	v_and_b32_e32 v108, 0xffff0000, v71
	s_cselect_b64 s[14:15], -1, 0
	s_and_b64 vcc, exec, s[12:13]
	v_mul_f32_e32 v108, v247, v108
	v_cvt_pk_bf16_f32 v107, v107, v108
	ds_write_b128 v228, v[104:107]
	s_waitcnt lgkmcnt(0)
	s_barrier
	s_cbranch_vccnz .Lret_last
	s_sub_i32 s11, s49, s51
	s_and_b64 s[34:35], s[0:1], exec
	s_cselect_b32 s11, s51, s11
	s_lshl_b32 s11, s11, 7
	s_add_i32 s53, s11, s48
	v_add_u32_e32 v0, s53, v236
	v_mov_b64_e32 v[64:65], s[42:43]
	v_mad_i64_i32 v[0:1], s[34:35], v0, s69, v[64:65]
	v_lshl_add_u64 v[0:1], v[0:1], 0, s[46:47]
	v_add_u32_e32 v2, s53, v237
	v_lshl_add_u64 v[0:1], v[0:1], 0, v[144:145]
	v_mad_i64_i32 v[2:3], s[34:35], v2, s69, v[64:65]
	v_add_co_u32_e32 v0, vcc, s68, v0
	v_lshl_add_u64 v[2:3], v[2:3], 0, s[46:47]
	v_add_u32_e32 v8, s53, v238
	v_addc_co_u32_e32 v1, vcc, 0, v1, vcc
	v_lshl_add_u64 v[2:3], v[2:3], 0, v[144:145]
	v_mad_i64_i32 v[8:9], s[34:35], v8, s69, v[64:65]
	v_add_co_u32_e32 v4, vcc, s68, v2
	v_lshl_add_u64 v[8:9], v[8:9], 0, s[46:47]
	v_add_u32_e32 v10, s53, v239
	v_addc_co_u32_e32 v5, vcc, 0, v3, vcc
	v_lshl_add_u64 v[8:9], v[8:9], 0, v[144:145]
	v_mad_i64_i32 v[10:11], s[34:35], v10, s69, v[64:65]
	v_add_co_u32_e32 v8, vcc, s68, v8
	v_lshl_add_u64 v[10:11], v[10:11], 0, s[46:47]
	v_add_u32_e32 v28, s53, v240
	v_addc_co_u32_e32 v9, vcc, 0, v9, vcc
	v_lshl_add_u64 v[10:11], v[10:11], 0, v[144:145]
	v_mad_i64_i32 v[28:29], s[34:35], v28, s69, v[64:65]
	v_add_co_u32_e32 v12, vcc, s68, v10
	v_lshl_add_u64 v[28:29], v[28:29], 0, s[46:47]
	v_add_u32_e32 v30, s53, v241
	v_addc_co_u32_e32 v13, vcc, 0, v11, vcc
	v_lshl_add_u64 v[28:29], v[28:29], 0, v[144:145]
	v_mad_i64_i32 v[30:31], s[34:35], v30, s69, v[64:65]
	v_add_co_u32_e32 v28, vcc, s68, v28
	v_lshl_add_u64 v[30:31], v[30:31], 0, s[46:47]
	v_add_u32_e32 v56, s53, v242
	v_addc_co_u32_e32 v29, vcc, 0, v29, vcc
	v_lshl_add_u64 v[30:31], v[30:31], 0, v[144:145]
	v_mad_i64_i32 v[56:57], s[34:35], v56, s69, v[64:65]
	v_add_co_u32_e32 v44, vcc, s68, v30
	v_lshl_add_u64 v[56:57], v[56:57], 0, s[46:47]
	v_add_u32_e32 v58, s53, v243
	v_addc_co_u32_e32 v45, vcc, 0, v31, vcc
	v_lshl_add_u64 v[56:57], v[56:57], 0, v[144:145]
	v_mad_i64_i32 v[58:59], s[34:35], v58, s69, v[64:65]
	v_add_u32_e32 v66, s53, v244
	v_add_co_u32_e32 v56, vcc, s68, v56
	v_lshl_add_u64 v[58:59], v[58:59], 0, s[46:47]
	v_mad_i64_i32 v[66:67], s[34:35], v66, s69, v[64:65]
	v_addc_co_u32_e32 v57, vcc, 0, v57, vcc
	v_lshl_add_u64 v[58:59], v[58:59], 0, v[144:145]
	v_lshl_add_u64 v[66:67], v[66:67], 0, s[46:47]
	s_mov_b32 s11, s47
	v_add_u32_e32 v68, s53, v245
	v_add_co_u32_e32 v60, vcc, s68, v58
	v_lshl_add_u64 v[66:67], v[66:67], 0, s[10:11]
	v_mov_b32_e32 v157, v145
	v_mad_i64_i32 v[64:65], s[34:35], v68, s69, v[64:65]
	v_addc_co_u32_e32 v61, vcc, 0, v59, vcc
	v_lshl_add_u64 v[66:67], v[66:67], 0, v[156:157]
	v_lshl_add_u64 v[64:65], v[64:65], 0, s[46:47]
	v_add_co_u32_e32 v66, vcc, 0x2000, v66
	v_lshl_add_u64 v[64:65], v[64:65], 0, s[10:11]
	s_nop 0
	v_addc_co_u32_e32 v67, vcc, 0, v67, vcc
	v_lshl_add_u64 v[64:65], v[64:65], 0, v[156:157]
	v_add_co_u32_e32 v68, vcc, 0x2000, v64
	global_load_dwordx4 v[0:3], v[0:1], off
	s_nop 0
	global_load_dwordx4 v[4:7], v[4:5], off
	v_addc_co_u32_e32 v69, vcc, 0, v65, vcc
	global_load_dwordx4 v[8:11], v[8:9], off
	s_nop 0
	global_load_dwordx4 v[12:15], v[12:13], off
	s_nop 0
	global_load_dwordx4 v[28:31], v[28:29], off
	s_nop 0
	global_load_dwordx4 v[44:47], v[44:45], off
	s_nop 0
	global_load_dwordx4 v[56:59], v[56:57], off
	s_nop 0
	global_load_dwordx4 v[60:63], v[60:61], off
	s_nop 0
	global_load_dwordx4 v[64:67], v[66:67], off nt
	s_nop 0
	global_load_dwordx4 v[68:71], v[68:69], off nt
	s_waitcnt vmcnt(10)
	s_branch .LBB0_119
.Lret_last:
	s_waitcnt vmcnt(0)
.LBB0_119:
	s_cmp_eq_u32 s52, 0
	s_cselect_b64 s[34:35], -1, 0
	s_xor_b64 s[54:55], s[6:7], -1
	s_and_b64 s[34:35], s[54:55], s[34:35]
	v_mov_b32_e32 v116, 0
	s_and_b64 vcc, exec, s[34:35]
	v_mov_b32_e32 v117, 0
	v_mov_b32_e32 v118, 0
	v_mov_b32_e32 v119, 0
	v_mov_b32_e32 v112, 0
	v_mov_b32_e32 v113, 0
	v_mov_b32_e32 v114, 0
	v_mov_b32_e32 v115, 0
	v_mov_b32_e32 v108, 0
	v_mov_b32_e32 v109, 0
	v_mov_b32_e32 v110, 0
	v_mov_b32_e32 v111, 0
	v_mov_b32_e32 v104, 0
	v_mov_b32_e32 v105, 0
	v_mov_b32_e32 v106, 0
	v_mov_b32_e32 v107, 0
	s_cbranch_vccnz .LBB0_121
	ds_read_b64_tr_b16 v[104:105], v209
	ds_read_b64_tr_b16 v[108:109], v209 offset:32
	ds_read_b64_tr_b16 v[112:113], v209 offset:64
	ds_read_b64_tr_b16 v[116:117], v209 offset:96
	ds_read_b64_tr_b16 v[106:107], v209 offset:2560
	ds_read_b64_tr_b16 v[110:111], v209 offset:2592
	ds_read_b64_tr_b16 v[114:115], v209 offset:2624
	ds_read_b64_tr_b16 v[118:119], v209 offset:2656
	s_waitcnt lgkmcnt(3)
	v_mfma_f32_16x16x32_bf16 v[104:107], v[104:107], v[16:19], 0
	s_waitcnt lgkmcnt(2)
	v_mfma_f32_16x16x32_bf16 v[108:111], v[108:111], v[16:19], 0
	s_waitcnt lgkmcnt(1)
	v_mfma_f32_16x16x32_bf16 v[112:115], v[112:115], v[16:19], 0
	s_waitcnt lgkmcnt(0)
	v_mfma_f32_16x16x32_bf16 v[116:119], v[116:119], v[16:19], 0
	ds_read_b64_tr_b16 v[120:121], v209 offset:5120
	ds_read_b64_tr_b16 v[124:125], v209 offset:5152
	ds_read_b64_tr_b16 v[128:129], v209 offset:5184
	ds_read_b64_tr_b16 v[132:133], v209 offset:5216
	ds_read_b64_tr_b16 v[122:123], v209 offset:7680
	ds_read_b64_tr_b16 v[126:127], v209 offset:7712
	ds_read_b64_tr_b16 v[130:131], v209 offset:7744
	ds_read_b64_tr_b16 v[134:135], v209 offset:7776
	s_waitcnt lgkmcnt(3)
	v_mfma_f32_16x16x32_bf16 v[104:107], v[120:123], v[20:23], v[104:107]
	s_waitcnt lgkmcnt(2)
	v_mfma_f32_16x16x32_bf16 v[108:111], v[124:127], v[20:23], v[108:111]
	s_waitcnt lgkmcnt(1)
	v_mfma_f32_16x16x32_bf16 v[112:115], v[128:131], v[20:23], v[112:115]
	s_waitcnt lgkmcnt(0)
	v_mfma_f32_16x16x32_bf16 v[116:119], v[132:135], v[20:23], v[116:119]
	ds_read_b64_tr_b16 v[120:121], v209 offset:10240
	ds_read_b64_tr_b16 v[124:125], v209 offset:10272
	ds_read_b64_tr_b16 v[128:129], v209 offset:10304
	ds_read_b64_tr_b16 v[132:133], v209 offset:10336
	ds_read_b64_tr_b16 v[122:123], v209 offset:12800
	ds_read_b64_tr_b16 v[126:127], v209 offset:12832
	ds_read_b64_tr_b16 v[130:131], v209 offset:12864
	ds_read_b64_tr_b16 v[134:135], v209 offset:12896
	s_waitcnt lgkmcnt(3)
	v_mfma_f32_16x16x32_bf16 v[104:107], v[120:123], v[24:27], v[104:107]
	s_waitcnt lgkmcnt(2)
	v_mfma_f32_16x16x32_bf16 v[108:111], v[124:127], v[24:27], v[108:111]
	s_waitcnt lgkmcnt(1)
	v_mfma_f32_16x16x32_bf16 v[112:115], v[128:131], v[24:27], v[112:115]
	s_waitcnt lgkmcnt(0)
	v_mfma_f32_16x16x32_bf16 v[116:119], v[132:135], v[24:27], v[116:119]
	ds_read_b64_tr_b16 v[120:121], v209 offset:15360
	ds_read_b64_tr_b16 v[124:125], v209 offset:15392
	ds_read_b64_tr_b16 v[128:129], v209 offset:15424
	ds_read_b64_tr_b16 v[132:133], v209 offset:15456
	ds_read_b64_tr_b16 v[122:123], v209 offset:17920
	ds_read_b64_tr_b16 v[126:127], v209 offset:17952
	ds_read_b64_tr_b16 v[130:131], v209 offset:17984
	ds_read_b64_tr_b16 v[134:135], v209 offset:18016
	s_waitcnt lgkmcnt(3)
	v_mfma_f32_16x16x32_bf16 v[104:107], v[120:123], v[32:35], v[104:107]
	s_waitcnt lgkmcnt(2)
	v_mfma_f32_16x16x32_bf16 v[108:111], v[124:127], v[32:35], v[108:111]
	s_waitcnt lgkmcnt(1)
	v_mfma_f32_16x16x32_bf16 v[112:115], v[128:131], v[32:35], v[112:115]
	s_waitcnt lgkmcnt(0)
	v_mfma_f32_16x16x32_bf16 v[116:119], v[132:135], v[32:35], v[116:119]
	ds_read_b64_tr_b16 v[120:121], v209 offset:20480
	ds_read_b64_tr_b16 v[124:125], v209 offset:20512
	ds_read_b64_tr_b16 v[128:129], v209 offset:20544
	ds_read_b64_tr_b16 v[132:133], v209 offset:20576
	ds_read_b64_tr_b16 v[122:123], v209 offset:23040
	ds_read_b64_tr_b16 v[126:127], v209 offset:23072
	ds_read_b64_tr_b16 v[130:131], v209 offset:23104
	ds_read_b64_tr_b16 v[134:135], v209 offset:23136
	s_waitcnt lgkmcnt(3)
	v_mfma_f32_16x16x32_bf16 v[104:107], v[120:123], v[36:39], v[104:107]
	s_waitcnt lgkmcnt(2)
	v_mfma_f32_16x16x32_bf16 v[108:111], v[124:127], v[36:39], v[108:111]
	s_waitcnt lgkmcnt(1)
	v_mfma_f32_16x16x32_bf16 v[112:115], v[128:131], v[36:39], v[112:115]
	s_waitcnt lgkmcnt(0)
	v_mfma_f32_16x16x32_bf16 v[116:119], v[132:135], v[36:39], v[116:119]
	ds_read_b64_tr_b16 v[120:121], v209 offset:25600
	ds_read_b64_tr_b16 v[124:125], v209 offset:25632
	ds_read_b64_tr_b16 v[128:129], v209 offset:25664
	ds_read_b64_tr_b16 v[132:133], v209 offset:25696
	ds_read_b64_tr_b16 v[122:123], v209 offset:28160
	ds_read_b64_tr_b16 v[126:127], v209 offset:28192
	ds_read_b64_tr_b16 v[130:131], v209 offset:28224
	ds_read_b64_tr_b16 v[134:135], v209 offset:28256
	s_waitcnt lgkmcnt(3)
	v_mfma_f32_16x16x32_bf16 v[104:107], v[120:123], v[40:43], v[104:107]
	s_waitcnt lgkmcnt(2)
	v_mfma_f32_16x16x32_bf16 v[108:111], v[124:127], v[40:43], v[108:111]
	s_waitcnt lgkmcnt(1)
	v_mfma_f32_16x16x32_bf16 v[112:115], v[128:131], v[40:43], v[112:115]
	s_waitcnt lgkmcnt(0)
	v_mfma_f32_16x16x32_bf16 v[116:119], v[132:135], v[40:43], v[116:119]
	ds_read_b64_tr_b16 v[120:121], v209 offset:30720
	ds_read_b64_tr_b16 v[124:125], v209 offset:30752
	ds_read_b64_tr_b16 v[128:129], v209 offset:30784
	ds_read_b64_tr_b16 v[132:133], v209 offset:30816
	ds_read_b64_tr_b16 v[122:123], v209 offset:33280
	ds_read_b64_tr_b16 v[126:127], v209 offset:33312
	ds_read_b64_tr_b16 v[130:131], v209 offset:33344
	ds_read_b64_tr_b16 v[134:135], v209 offset:33376
	s_waitcnt lgkmcnt(3)
	v_mfma_f32_16x16x32_bf16 v[104:107], v[120:123], v[48:51], v[104:107]
	s_waitcnt lgkmcnt(2)
	v_mfma_f32_16x16x32_bf16 v[108:111], v[124:127], v[48:51], v[108:111]
	s_waitcnt lgkmcnt(1)
	v_mfma_f32_16x16x32_bf16 v[112:115], v[128:131], v[48:51], v[112:115]
	s_waitcnt lgkmcnt(0)
	v_mfma_f32_16x16x32_bf16 v[116:119], v[132:135], v[48:51], v[116:119]
	ds_read_b64_tr_b16 v[120:121], v209 offset:35840
	ds_read_b64_tr_b16 v[124:125], v209 offset:35872
	ds_read_b64_tr_b16 v[128:129], v209 offset:35904
	ds_read_b64_tr_b16 v[132:133], v209 offset:35936
	ds_read_b64_tr_b16 v[122:123], v209 offset:38400
	ds_read_b64_tr_b16 v[126:127], v209 offset:38432
	ds_read_b64_tr_b16 v[130:131], v209 offset:38464
	ds_read_b64_tr_b16 v[134:135], v209 offset:38496
	s_waitcnt lgkmcnt(3)
	v_mfma_f32_16x16x32_bf16 v[104:107], v[120:123], v[52:55], v[104:107]
	s_waitcnt lgkmcnt(2)
	v_mfma_f32_16x16x32_bf16 v[108:111], v[124:127], v[52:55], v[108:111]
	s_waitcnt lgkmcnt(1)
	v_mfma_f32_16x16x32_bf16 v[112:115], v[128:131], v[52:55], v[112:115]
	s_waitcnt lgkmcnt(0)
	v_mfma_f32_16x16x32_bf16 v[116:119], v[132:135], v[52:55], v[116:119]
